# postA row loop: next row of P touched into L2 one iteration ahead (two dword-per-lane loads, counted waits raised by two)
# baseline (speedup 1.0000x reference)
.LBB0_367:
	v_cvt_pk_bf16_f32 v140, v140, v141
	v_cvt_pk_bf16_f32 v141, v138, v139
	v_cvt_pk_bf16_f32 v142, v114, v115
	v_cvt_pk_bf16_f32 v143, v112, v113
	global_store_dwordx4 v[136:137], v[140:143], off offset:1024
	s_waitcnt vmcnt(11)
	v_lshlrev_b32_e32 v9, 16, v101
	v_and_b32_e32 v112, 0xffff0000, v101
	v_lshlrev_b32_e32 v113, 16, v102
	v_and_b32_e32 v114, 0xffff0000, v102
	v_lshlrev_b32_e32 v115, 16, v103
	v_and_b32_e32 v136, 0xffff0000, v103
	s_waitcnt vmcnt(6)
	v_lshlrev_b32_e32 v15, 16, v108
	v_and_b32_e32 v135, 0xffff0000, v108
	v_lshlrev_b32_e32 v17, 16, v109
	v_and_b32_e32 v133, 0xffff0000, v109
	v_lshlrev_b32_e32 v11, 16, v110
	v_and_b32_e32 v131, 0xffff0000, v110
	s_waitcnt vmcnt(5)
	v_lshlrev_b32_e32 v101, 16, v104
	v_and_b32_e32 v108, 0xffff0000, v104
	v_lshlrev_b32_e32 v109, 16, v105
	v_and_b32_e32 v110, 0xffff0000, v105
	v_cndmask_b32_e64 v137, 1.0, 0, s[70:71]
	v_lshlrev_b32_e32 v103, 16, v90
	v_lshlrev_b32_e32 v102, 16, v78
	v_lshlrev_b32_e32 v105, 16, v94
	v_lshlrev_b32_e32 v104, 16, v86
	v_mul_f32_e32 v3, v18, v137
	v_pk_mul_f32 v[102:103], v[102:103], v[104:105]
	v_lshlrev_b32_e32 v5, 16, v100
	v_and_b32_e32 v7, 0xffff0000, v100
	v_cndmask_b32_e64 v100, 0, 1.0, s[72:73]
	v_pk_mul_f32 v[102:103], v[2:3], v[102:103]
	v_pk_mul_f32 v[104:105], v[14:15], v[100:101]
	v_add_f32_e32 v3, v102, v103
	v_fmac_f32_e32 v3, v104, v105
	v_and_b32_e32 v103, 0xffff0000, v90
	v_and_b32_e32 v102, 0xffff0000, v78
	v_and_b32_e32 v105, 0xffff0000, v94
	v_and_b32_e32 v104, 0xffff0000, v86
	v_mul_f32_e32 v127, v19, v137
	v_pk_mul_f32 v[102:103], v[102:103], v[104:105]
	v_mov_b32_e32 v101, v108
	v_pk_mul_f32 v[102:103], v[126:127], v[102:103]
	v_mul_f32_e32 v3, v3, v5
	v_pk_mul_f32 v[104:105], v[134:135], v[100:101]
	v_add_f32_e32 v5, v102, v103
	v_lshlrev_b32_e32 v103, 16, v91
	v_lshlrev_b32_e32 v102, 16, v79
	v_and_b32_e32 v91, 0xffff0000, v91
	v_and_b32_e32 v90, 0xffff0000, v79
	v_and_b32_e32 v79, 0xffff0000, v95
	v_and_b32_e32 v78, 0xffff0000, v87
	v_fmac_f32_e32 v5, v104, v105
	v_lshlrev_b32_e32 v105, 16, v95
	v_lshlrev_b32_e32 v104, 16, v87
	v_mov_b32_e32 v101, v109
	v_mul_f32_e32 v125, v21, v137
	v_pk_mul_f32 v[78:79], v[90:91], v[78:79]
	v_pk_mul_f32 v[102:103], v[102:103], v[104:105]
	v_pk_mul_f32 v[104:105], v[16:17], v[100:101]
	v_pk_mul_f32 v[78:79], v[124:125], v[78:79]
	v_mov_b32_e32 v101, v110
	v_mul_f32_e32 v15, v5, v7
	v_pk_mul_f32 v[86:87], v[132:133], v[100:101]
	v_add_f32_e32 v7, v78, v79
	v_fmac_f32_e32 v7, v86, v87
	v_lshlrev_b32_e32 v79, 16, v92
	v_lshlrev_b32_e32 v78, 16, v80
	v_lshlrev_b32_e32 v87, 16, v96
	v_lshlrev_b32_e32 v86, 16, v88
	v_lshlrev_b32_e32 v13, 16, v111
	v_and_b32_e32 v129, 0xffff0000, v111
	v_lshlrev_b32_e32 v111, 16, v106
	v_mul_f32_e32 v17, v7, v112
	v_mul_f32_e32 v7, v22, v137
	v_pk_mul_f32 v[78:79], v[78:79], v[86:87]
	v_mov_b32_e32 v101, v111
	v_pk_mul_f32 v[78:79], v[6:7], v[78:79]
	v_mul_f32_e32 v5, v20, v137
	v_pk_mul_f32 v[86:87], v[10:11], v[100:101]
	v_add_f32_e32 v7, v78, v79
	v_pk_mul_f32 v[102:103], v[4:5], v[102:103]
	v_fmac_f32_e32 v7, v86, v87
	v_and_b32_e32 v79, 0xffff0000, v92
	v_and_b32_e32 v78, 0xffff0000, v80
	v_and_b32_e32 v87, 0xffff0000, v96
	v_and_b32_e32 v86, 0xffff0000, v88
	v_and_b32_e32 v106, 0xffff0000, v106
	v_add_f32_e32 v5, v102, v103
	v_mul_f32_e32 v123, v23, v137
	v_pk_mul_f32 v[78:79], v[78:79], v[86:87]
	v_fmac_f32_e32 v5, v104, v105
	v_pk_mul_f32 v[78:79], v[122:123], v[78:79]
	v_mov_b32_e32 v101, v106
	v_mul_f32_e32 v5, v5, v9
	v_pk_mul_f32 v[86:87], v[130:131], v[100:101]
	v_add_f32_e32 v9, v78, v79
	v_fmac_f32_e32 v9, v86, v87
	v_lshlrev_b32_e32 v79, 16, v93
	v_lshlrev_b32_e32 v78, 16, v81
	v_lshlrev_b32_e32 v87, 16, v97
	v_lshlrev_b32_e32 v86, 16, v89
	v_mul_f32_e32 v11, v9, v114
	v_mul_f32_e32 v9, v24, v137
	v_pk_mul_f32 v[78:79], v[78:79], v[86:87]
	v_lshlrev_b32_e32 v121, 16, v107
	v_pk_mul_f32 v[78:79], v[8:9], v[78:79]
	v_and_b32_e32 v80, 0xffff0000, v89
	v_add_f32_e32 v9, v78, v79
	v_and_b32_e32 v79, 0xffff0000, v93
	v_and_b32_e32 v78, 0xffff0000, v81
	v_and_b32_e32 v81, 0xffff0000, v97
	v_and_b32_e32 v107, 0xffff0000, v107
	v_mov_b32_e32 v101, v121
	v_mul_f32_e32 v121, v25, v137
	v_pk_mul_f32 v[78:79], v[78:79], v[80:81]
	v_pk_mul_f32 v[86:87], v[12:13], v[100:101]
	v_pk_mul_f32 v[78:79], v[120:121], v[78:79]
	v_mov_b32_e32 v101, v107
	v_pk_mul_f32 v[80:81], v[128:129], v[100:101]
	v_add_f32_e32 v13, v78, v79
	v_fmac_f32_e32 v13, v80, v81
	v_fmac_f32_e32 v9, v86, v87
	v_mul_f32_e32 v13, v13, v136
	v_cvt_pk_bf16_f32 v78, v3, v15
	v_cvt_pk_bf16_f32 v79, v5, v17
	s_waitcnt vmcnt(4)
	v_and_b32_e32 v5, 0xffff0000, v82
	v_mul_f32_e32 v7, v7, v113
	v_mul_f32_e32 v9, v9, v115
	v_cvt_pk_bf16_f32 v80, v7, v11
	v_cvt_pk_bf16_f32 v81, v9, v13
	v_lshlrev_b32_e32 v11, 16, v84
	v_and_b32_e32 v13, 0xffff0000, v84
	v_mul_f32_e32 v84, 0x3d372713, v5
	v_mul_f32_e32 v84, v84, v5
	v_fma_f32 v84, v84, v5, v5
	v_lshl_add_u64 v[86:87], s[62:63], 0, v[98:99]
	v_mul_f32_e32 v84, 0xbfcc422a, v84
	global_store_dwordx4 v[86:87], v[78:81], off
	v_mul_f32_e32 v84, 0x3fb8aa3b, v84
	v_exp_f32_e32 v84, v84
	v_lshlrev_b32_e32 v79, 16, v75
	v_and_b32_e32 v75, 0xffff0000, v75
	v_mul_f32_e32 v87, 0x3d372713, v75
	v_mul_f32_e32 v87, v87, v75
	v_fma_f32 v87, v87, v75, v75
	v_mul_f32_e32 v87, 0xbfcc422a, v87
	v_lshlrev_b32_e32 v3, 16, v82
	v_lshlrev_b32_e32 v78, 16, v74
	v_add_f32_e32 v84, 1.0, v84
	v_mul_f32_e32 v87, 0x3fb8aa3b, v87
	v_and_b32_e32 v74, 0xffff0000, v74
	v_mul_f32_e32 v81, 0x3d372713, v3
	v_mul_f32_e32 v82, 0x3d372713, v78
	v_rcp_f32_e32 v84, v84
	v_exp_f32_e32 v87, v87
	v_lshlrev_b32_e32 v15, 16, v85
	v_and_b32_e32 v17, 0xffff0000, v85
	v_mul_f32_e32 v81, v81, v3
	v_mul_f32_e32 v82, v82, v78
	v_mul_f32_e32 v85, 0x3d372713, v74
	v_fma_f32 v81, v81, v3, v3
	v_fma_f32 v82, v82, v78, v78
	v_mul_f32_e32 v85, v85, v74
	v_mul_f32_e32 v86, 0x3d372713, v79
	v_lshlrev_b32_e32 v80, 16, v76
	v_mul_f32_e32 v81, 0xbfcc422a, v81
	v_mul_f32_e32 v82, 0xbfcc422a, v82
	v_fma_f32 v85, v85, v74, v74
	v_mul_f32_e32 v86, v86, v79
	v_and_b32_e32 v76, 0xffff0000, v76
	v_mul_f32_e32 v81, 0x3fb8aa3b, v81
	v_mul_f32_e32 v82, 0x3fb8aa3b, v82
	v_mul_f32_e32 v85, 0xbfcc422a, v85
	v_fma_f32 v86, v86, v79, v79
	v_mul_f32_e32 v5, v84, v5
	v_add_f32_e32 v84, 1.0, v87
	v_mul_f32_e32 v87, 0x3d372713, v80
	v_lshlrev_b32_e32 v7, 16, v83
	v_and_b32_e32 v9, 0xffff0000, v83
	v_exp_f32_e32 v81, v81
	v_exp_f32_e32 v82, v82
	v_lshlrev_b32_e32 v83, 16, v77
	v_mul_f32_e32 v85, 0x3fb8aa3b, v85
	v_mul_f32_e32 v86, 0xbfcc422a, v86
	v_mul_f32_e32 v87, v87, v80
	v_mul_f32_e32 v88, 0x3d372713, v76
	v_and_b32_e32 v77, 0xffff0000, v77
	v_exp_f32_e32 v85, v85
	v_mul_f32_e32 v86, 0x3fb8aa3b, v86
	v_fma_f32 v87, v87, v80, v80
	v_mul_f32_e32 v88, v88, v76
	v_mul_f32_e32 v89, 0x3d372713, v83
	v_exp_f32_e32 v86, v86
	v_mul_f32_e32 v87, 0xbfcc422a, v87
	v_fma_f32 v88, v88, v76, v76
	v_mul_f32_e32 v89, v89, v83
	v_mul_f32_e32 v90, 0x3d372713, v77
	v_mul_f32_e32 v87, 0x3fb8aa3b, v87
	v_mul_f32_e32 v88, 0xbfcc422a, v88
	v_fma_f32 v89, v89, v83, v83
	v_mul_f32_e32 v90, v90, v77
	v_add_f32_e32 v81, 1.0, v81
	v_add_f32_e32 v82, 1.0, v82
	v_exp_f32_e32 v87, v87
	v_mul_f32_e32 v88, 0x3fb8aa3b, v88
	v_mul_f32_e32 v89, 0xbfcc422a, v89
	v_fma_f32 v90, v90, v77, v77
	v_rcp_f32_e32 v81, v81
	v_rcp_f32_e32 v82, v82
	v_add_f32_e32 v85, 1.0, v85
	v_exp_f32_e32 v88, v88
	v_mul_f32_e32 v89, 0x3fb8aa3b, v89
	v_mul_f32_e32 v90, 0xbfcc422a, v90
	v_rcp_f32_e32 v85, v85
	v_add_f32_e32 v86, 1.0, v86
	v_exp_f32_e32 v89, v89
	v_mul_f32_e32 v90, 0x3fb8aa3b, v90
	v_rcp_f32_e32 v86, v86
	v_exp_f32_e32 v90, v90
	v_rcp_f32_e32 v84, v84
	v_add_f32_e32 v87, 1.0, v87
	v_mul_f32_e32 v3, v81, v3
	v_fma_f32 v81, v82, v78, 0
	v_rcp_f32_e32 v87, v87
	v_add_f32_e32 v88, 1.0, v88
	v_fmac_f32_e32 v81, v85, v74
	v_rcp_f32_e32 v88, v88
	v_add_f32_e32 v89, 1.0, v89
	v_fmac_f32_e32 v81, v86, v79
	v_rcp_f32_e32 v89, v89
	v_add_f32_e32 v90, 1.0, v90
	v_fmac_f32_e32 v81, v84, v75
	v_rcp_f32_e32 v90, v90
	v_fmac_f32_e32 v81, v87, v80
	v_fmac_f32_e32 v81, v88, v76
	v_fmac_f32_e32 v81, v89, v83
	v_fmac_f32_e32 v81, v90, v77
	ds_bpermute_b32 v91, v147, v81
	v_mul_f32_e32 v92, 0x3d372713, v7
	v_mul_f32_e32 v92, v92, v7
	v_fma_f32 v92, v92, v7, v7
	v_mul_f32_e32 v92, 0xbfcc422a, v92
	s_waitcnt lgkmcnt(0)
	v_add_f32_e32 v81, v81, v91
	ds_bpermute_b32 v91, v148, v81
	v_mul_f32_e32 v92, 0x3fb8aa3b, v92
	v_exp_f32_e32 v92, v92
	v_mul_f32_e32 v93, 0x3d372713, v9
	v_mul_f32_e32 v93, v93, v9
	s_waitcnt lgkmcnt(0)
	v_add_f32_e32 v81, v81, v91
	ds_bpermute_b32 v91, v149, v81
	v_add_f32_e32 v92, 1.0, v92
	v_rcp_f32_e32 v92, v92
	v_fma_f32 v93, v93, v9, v9
	v_mul_f32_e32 v93, 0xbfcc422a, v93
	s_waitcnt lgkmcnt(0)
	v_add_f32_e32 v81, v81, v91
	ds_bpermute_b32 v91, v150, v81
	v_mul_f32_e32 v7, v92, v7
	v_mul_f32_e32 v92, 0x3d372713, v11
	v_mul_f32_e32 v92, v92, v11
	v_fma_f32 v92, v92, v11, v11
	s_waitcnt lgkmcnt(0)
	v_add_f32_e32 v81, v81, v91
	ds_bpermute_b32 v91, v151, v81
	v_mul_f32_e32 v92, 0xbfcc422a, v92
	v_mul_f32_e32 v92, 0x3fb8aa3b, v92
	v_exp_f32_e32 v92, v92
	v_mul_f32_e32 v93, 0x3fb8aa3b, v93
	s_waitcnt lgkmcnt(0)
	v_add_f32_e32 v81, v81, v91
	ds_bpermute_b32 v91, v152, v81
	v_exp_f32_e32 v93, v93
	s_waitcnt lgkmcnt(0)
	v_add_f32_e32 v81, v81, v91
	v_mul_f32_e32 v81, 0x3b000000, v81
	v_fma_f32 v74, v85, v74, -v81
	v_fma_f32 v78, v82, v78, -v81
	v_mul_f32_e32 v82, v74, v74
	v_fmac_f32_e32 v82, v78, v78
	v_fma_f32 v79, v86, v79, -v81
	v_fmac_f32_e32 v82, v79, v79
	v_fma_f32 v75, v84, v75, -v81
	v_fmac_f32_e32 v82, v75, v75
	v_fma_f32 v80, v87, v80, -v81
	v_fmac_f32_e32 v82, v80, v80
	v_fma_f32 v76, v88, v76, -v81
	v_fmac_f32_e32 v82, v76, v76
	v_fma_f32 v83, v89, v83, -v81
	v_fmac_f32_e32 v82, v83, v83
	v_fma_f32 v77, v90, v77, -v81
	v_fmac_f32_e32 v82, v77, v77
	ds_bpermute_b32 v81, v147, v82
	v_mul_f32_e32 v85, 0x3d372713, v13
	v_mul_f32_e32 v85, v85, v13
	v_fma_f32 v85, v85, v13, v13
	v_mul_f32_e32 v85, 0xbfcc422a, v85
	s_waitcnt lgkmcnt(0)
	v_add_f32_e32 v81, v82, v81
	ds_bpermute_b32 v82, v148, v81
	v_add_f32_e32 v84, 1.0, v92
	v_mul_f32_e32 v85, 0x3fb8aa3b, v85
	v_rcp_f32_e32 v84, v84
	v_exp_f32_e32 v85, v85
	s_waitcnt lgkmcnt(0)
	v_add_f32_e32 v81, v81, v82
	ds_bpermute_b32 v82, v149, v81
	v_mul_f32_e32 v11, v84, v11
	v_add_f32_e32 v84, 1.0, v85
	v_mul_f32_e32 v85, 0x3d372713, v15
	v_mul_f32_e32 v85, v85, v15
	s_waitcnt lgkmcnt(0)
	v_add_f32_e32 v81, v81, v82
	ds_bpermute_b32 v82, v150, v81
	v_mul_f32_e32 v86, 0x3d372713, v17
	v_fma_f32 v85, v85, v15, v15
	v_mul_f32_e32 v86, v86, v17
	v_mul_f32_e32 v85, 0xbfcc422a, v85
	s_waitcnt lgkmcnt(0)
	v_add_f32_e32 v81, v81, v82
	ds_bpermute_b32 v82, v151, v81
	v_fma_f32 v86, v86, v17, v17
	v_mul_f32_e32 v85, 0x3fb8aa3b, v85
	v_mul_f32_e32 v86, 0xbfcc422a, v86
	v_exp_f32_e32 v85, v85
	s_waitcnt lgkmcnt(0)
	v_add_f32_e32 v81, v81, v82
	ds_bpermute_b32 v82, v152, v81
	v_mul_f32_e32 v86, 0x3fb8aa3b, v86
	v_exp_f32_e32 v86, v86
	v_rcp_f32_e32 v84, v84
	v_add_f32_e32 v85, 1.0, v85
	s_waitcnt lgkmcnt(0)
	v_add_f32_e32 v81, v81, v82
	v_fmamk_f32 v81, v81, 0x3b000000, v224
	v_mul_f32_e32 v82, 0x4f800000, v81
	v_cmp_gt_f32_e32 vcc, s33, v81
	v_rcp_f32_e32 v85, v85
	v_add_f32_e32 v86, 1.0, v86
	v_cndmask_b32_e32 v81, v81, v82, vcc
	v_sqrt_f32_e32 v82, v81
	v_rcp_f32_e32 v86, v86
	v_mul_f32_e32 v13, v84, v13
	v_mul_f32_e32 v15, v85, v15
	v_add_u32_e32 v87, -1, v82
	v_fma_f32 v88, -v87, v82, v81
	v_cmp_ge_f32_e64 s[46:47], 0, v88
	v_add_u32_e32 v88, 1, v82
	v_mul_f32_e32 v17, v86, v17
	v_cndmask_b32_e64 v87, v82, v87, s[46:47]
	v_fma_f32 v82, -v88, v82, v81
	v_cmp_lt_f32_e64 s[46:47], 0, v82
	v_add_f32_e32 v93, 1.0, v93
	v_rcp_f32_e32 v93, v93
	v_cndmask_b32_e64 v82, v87, v88, s[46:47]
	v_mul_f32_e32 v87, 0x37800000, v82
	v_cndmask_b32_e32 v82, v82, v87, vcc
	v_cmp_class_f32_e32 vcc, v81, v225
	v_mul_f32_e32 v9, v93, v9
	s_nop 0
	v_cndmask_b32_e32 v81, v82, v81, vcc
	v_div_scale_f32 v82, s[6:7], v81, v81, 1.0
	v_rcp_f32_e32 v87, v82
	s_nop 0
	v_fma_f32 v84, -v82, v87, 1.0
	v_fmac_f32_e32 v87, v84, v87
	v_div_scale_f32 v84, vcc, 1.0, v81, 1.0
	v_mul_f32_e32 v85, v84, v87
	v_fma_f32 v86, -v82, v85, v84
	v_fmac_f32_e32 v85, v86, v87
	v_fma_f32 v82, -v82, v85, v84
	v_div_fmas_f32 v82, v82, v87, v85
	v_div_fixup_f32 v81, v82, v81, 1.0
	v_mul_f32_e32 v74, v74, v81
	v_fma_f32 v84, v27, v74, v35
	v_mul_f32_e32 v74, v79, v81
	v_fma_f32 v85, v28, v74, v36
	v_mul_f32_e32 v74, v75, v81
	v_mul_f32_e32 v78, v78, v81
	v_fma_f32 v86, v29, v74, v37
	v_mul_f32_e32 v74, v80, v81
	v_fma_f32 v82, v26, v78, v34
	v_fma_f32 v87, v30, v74, v38
	v_mul_f32_e32 v74, v76, v81
	v_lshl_add_u64 v[78:79], s[58:59], 0, v[98:99]
	v_fma_f32 v88, v31, v74, v39
	v_mul_f32_e32 v74, v83, v81
	v_add_co_u32_e32 v80, vcc, 0x37224000, v78
	v_fma_f32 v83, v32, v74, v40
	v_mul_f32_e32 v74, v77, v81
	v_addc_co_u32_e32 v81, vcc, 0, v79, vcc
	v_add_co_u32_e32 v78, vcc, 0x38324000, v78
	v_fma_f32 v89, v33, v74, v41
	v_cvt_pk_bf16_f32 v74, v3, v5
	v_cvt_pk_bf16_f32 v75, v7, v9
	v_cvt_pk_bf16_f32 v76, v11, v13
	v_cvt_pk_bf16_f32 v77, v15, v17
	s_nop 0
	v_addc_co_u32_e32 v79, vcc, 0, v79, vcc
	global_store_dwordx4 v[80:81], v[74:77], off
	s_nop 1
	v_cvt_pk_bf16_f32 v74, v82, v84
	v_cvt_pk_bf16_f32 v75, v85, v86
	v_cvt_pk_bf16_f32 v76, v87, v88
	v_cvt_pk_bf16_f32 v77, v83, v89
	global_store_dwordx4 v[78:79], v[74:77], off

.LBB0_378:
	v_add_co_u32_e32 v78, vcc, 0x21e24000, v82
	s_and_b64 s[8:9], exec, s[48:49]
	s_nop 0
	v_addc_co_u32_e32 v79, vcc, 0, v83, vcc
	global_load_dwordx4 v[136:139], v[78:79], off
	s_mov_b32 s7, 0x21e26000
	v_add_co_u32_e32 v84, vcc, s7, v82
	s_movk_i32 s7, 0xfff
	s_cselect_b32 s5, s6, s5
	s_cselect_b32 s8, 0xff, s7
	s_cmp_eq_u32 s5, 0
	s_cselect_b64 s[70:71], -1, 0
	s_and_b64 s[6:7], s[70:71], exec
	v_addc_co_u32_e32 v85, vcc, 0, v83, vcc
	s_cselect_b32 s6, 0, 0xffffd800
	s_cselect_b32 s7, 0, -1
	s_cmp_lt_u32 s5, s8
	v_add_co_u32_e32 v86, vcc, 0x21e25000, v82
	s_cselect_b64 s[72:73], -1, 0
	s_nop 0
	v_addc_co_u32_e32 v87, vcc, 0, v83, vcc
	v_lshl_add_u64 v[88:89], v[82:83], 0, s[6:7]
	s_and_b64 s[6:7], s[72:73], exec
	s_mov_b32 s5, 0x21e25000
	v_add_co_u32_e32 v94, vcc, s5, v88
	s_cselect_b32 s52, 0x2800, 0
	s_nop 0
	v_addc_co_u32_e32 v95, vcc, 0, v89, vcc
	v_lshl_add_u64 v[82:83], v[82:83], 0, s[52:53]
	v_add_co_u32_e32 v82, vcc, s5, v82
	global_load_dwordx4 v[74:77], v[84:85], off offset:1024
	global_load_dwordx4 v[112:115], v[78:79], off offset:1024
	v_addc_co_u32_e32 v83, vcc, 0, v83, vcc
	global_load_dwordx4 v[100:103], v[86:87], off offset:1024
	global_load_dwordx4 v[78:81], v[86:87], off offset:2048
	s_nop 0
	global_load_dwordx4 v[86:89], v[86:87], off offset:3072
	s_nop 0
	global_load_dwordx4 v[90:93], v[94:95], off offset:2048
	s_nop 0
	global_load_dwordx4 v[94:97], v[94:95], off offset:3072
	s_nop 0
	global_load_dwordx4 v[108:111], v[82:83], off offset:2048
	global_load_dwordx4 v[104:107], v[82:83], off offset:3072
	s_nop 0
	global_load_dwordx4 v[82:85], v[84:85], off
	v_and_b32_e32 v162, 63, v0
	v_lshlrev_b32_e32 v162, 7, v162
	v_add_u32_e32 v162, 0x21e38000, v162
	v_mov_b32_e32 v163, 0
	v_lshl_add_u64 v[164:165], s[68:69], 0, v[162:163]
	global_load_dword v166, v[164:165], off
	v_add_u32_e32 v162, 0x2000, v162
	v_lshl_add_u64 v[164:165], s[68:69], 0, v[162:163]
	global_load_dword v167, v[164:165], off
	s_waitcnt vmcnt(12)
	v_lshlrev_b32_e32 v142, 16, v136
	v_and_b32_e32 v143, 0xffff0000, v136
	v_lshlrev_b32_e32 v136, 16, v137
	v_and_b32_e32 v137, 0xffff0000, v137
	v_pk_mul_f32 v[156:157], v[142:143], v[142:143]
	v_pk_mul_f32 v[158:159], v[136:137], v[136:137]
	v_add_f32_e32 v3, v156, v157
	v_lshlrev_b32_e32 v154, 16, v138
	v_and_b32_e32 v155, 0xffff0000, v138
	v_add_f32_e32 v3, v158, v3
	v_pk_mul_f32 v[160:161], v[154:155], v[154:155]
	v_add_f32_e32 v3, v159, v3
	v_and_b32_e32 v140, 0xffff0000, v139
	v_lshlrev_b32_e32 v141, 16, v139
	v_add_f32_e32 v3, v160, v3
	v_pk_mul_f32 v[138:139], v[140:141], v[140:141]
	v_add_f32_e32 v3, v161, v3
	v_add_f32_e32 v3, v139, v3
	v_add_f32_e32 v3, v138, v3
	ds_bpermute_b32 v5, v147, v3
	s_waitcnt lgkmcnt(0)
	v_add_f32_e32 v3, v3, v5
	ds_bpermute_b32 v5, v148, v3
	s_waitcnt lgkmcnt(0)
	v_add_f32_e32 v3, v3, v5
	ds_bpermute_b32 v5, v149, v3
	s_waitcnt lgkmcnt(0)
	v_add_f32_e32 v3, v3, v5
	ds_bpermute_b32 v5, v150, v3
	s_waitcnt lgkmcnt(0)
	v_add_f32_e32 v3, v3, v5
	v_fmamk_f32 v3, v3, 0x3c000000, v224
	v_mul_f32_e32 v5, 0x4f800000, v3
	v_cmp_gt_f32_e32 vcc, s33, v3
	s_nop 1
	v_cndmask_b32_e32 v3, v3, v5, vcc
	v_sqrt_f32_e32 v5, v3
	s_nop 0
	v_add_u32_e32 v7, -1, v5
	v_add_u32_e32 v9, 1, v5
	v_fma_f32 v11, -v7, v5, v3
	v_fma_f32 v13, -v9, v5, v3
	v_cmp_ge_f32_e64 s[48:49], 0, v11
	s_nop 1
	v_cndmask_b32_e64 v5, v5, v7, s[48:49]
	v_cmp_lt_f32_e64 s[48:49], 0, v13
	s_nop 1
	v_cndmask_b32_e64 v5, v5, v9, s[48:49]
	v_mul_f32_e32 v7, 0x37800000, v5
	v_cndmask_b32_e32 v5, v5, v7, vcc
	v_cmp_class_f32_e32 vcc, v3, v225
	s_nop 1
	v_cndmask_b32_e32 v3, v5, v3, vcc
	v_div_scale_f32 v5, s[6:7], v3, v3, 1.0
	v_rcp_f32_e32 v7, v5
	v_div_scale_f32 v9, vcc, 1.0, v3, 1.0
	v_fma_f32 v11, -v5, v7, 1.0
	v_fmac_f32_e32 v7, v11, v7
	v_mul_f32_e32 v11, v9, v7
	v_fma_f32 v13, -v5, v11, v9
	v_fmac_f32_e32 v11, v13, v7
	v_fma_f32 v5, -v5, v11, v9
	v_div_fmas_f32 v5, v5, v7, v11
	v_div_fixup_f32 v138, v5, v3, 1.0
	v_pk_mul_f32 v[142:143], v[138:139], v[142:143] op_sel_hi:[0,1]
	v_pk_mul_f32 v[156:157], v[138:139], v[136:137] op_sel_hi:[0,1]
	v_pk_mul_f32 v[154:155], v[138:139], v[154:155] op_sel_hi:[0,1]
	v_pk_mul_f32 v[158:159], v[138:139], v[140:141] op_sel_hi:[0,1]
	s_and_b64 vcc, exec, s[46:47]
	v_pk_mul_f32 v[136:137], v[46:47], v[142:143]
	v_pk_mul_f32 v[138:139], v[48:49], v[156:157]
	v_pk_mul_f32 v[140:141], v[42:43], v[154:155]
	v_pk_mul_f32 v[142:143], v[44:45], v[158:159] op_sel:[0,1] op_sel_hi:[1,0]
	s_cbranch_vccnz .LBB0_380
	ds_bpermute_b32 v154, v149, v136
	ds_bpermute_b32 v155, v149, v137
	v_mov_b32_e32 v158, v59
	v_mov_b32_e32 v159, v61
	v_mov_b32_e32 v156, v58
	v_mov_b32_e32 v157, v60
	s_waitcnt lgkmcnt(0)
	v_pk_mul_f32 v[154:155], v[158:159], v[154:155]
	v_mov_b32_e32 v158, v63
	v_cndmask_b32_e64 v155, v155, -v155, s[42:43]
	v_cndmask_b32_e64 v154, v154, -v154, s[42:43]
	v_pk_fma_f32 v[136:137], v[156:157], v[136:137], v[154:155]
	ds_bpermute_b32 v154, v149, v138
	ds_bpermute_b32 v155, v149, v139
	v_mov_b32_e32 v159, v65
	v_mov_b32_e32 v156, v62
	v_mov_b32_e32 v157, v64
	s_waitcnt lgkmcnt(0)
	v_pk_mul_f32 v[154:155], v[158:159], v[154:155]
	s_nop 0
	v_cndmask_b32_e64 v155, v155, -v155, s[42:43]
	v_cndmask_b32_e64 v154, v154, -v154, s[42:43]
	v_pk_fma_f32 v[138:139], v[156:157], v[138:139], v[154:155]
	ds_bpermute_b32 v154, v149, v140
	ds_bpermute_b32 v155, v149, v141
	v_mov_b32_e32 v158, v67
	v_mov_b32_e32 v159, v69
	v_mov_b32_e32 v156, v66
	v_mov_b32_e32 v157, v68
	s_waitcnt lgkmcnt(0)
	v_pk_mul_f32 v[154:155], v[158:159], v[154:155]
	v_mov_b32_e32 v158, v71
	v_cndmask_b32_e64 v155, v155, -v155, s[42:43]
	v_cndmask_b32_e64 v154, v154, -v154, s[42:43]
	v_pk_fma_f32 v[140:141], v[156:157], v[140:141], v[154:155]
	ds_bpermute_b32 v154, v149, v142
	ds_bpermute_b32 v155, v149, v143
	v_mov_b32_e32 v159, v73
	v_mov_b32_e32 v156, v70
	v_mov_b32_e32 v157, v72
	s_waitcnt lgkmcnt(0)
	v_pk_mul_f32 v[154:155], v[158:159], v[154:155]
	s_nop 0
	v_cndmask_b32_e64 v155, v155, -v155, s[42:43]
	v_cndmask_b32_e64 v154, v154, -v154, s[42:43]
	v_pk_fma_f32 v[142:143], v[156:157], v[142:143], v[154:155]
.LBB0_380:
	v_lshl_add_u64 v[158:159], s[64:65], 0, v[98:99]
	s_mov_b32 s5, 0x35024000
	v_cvt_pk_bf16_f32 v154, v136, v137
	v_add_co_u32_e32 v136, vcc, s5, v158
	v_cvt_pk_bf16_f32 v155, v138, v139
	v_cvt_pk_bf16_f32 v156, v140, v141
	s_waitcnt vmcnt(10)
	v_lshlrev_b32_e32 v140, 16, v112
	v_addc_co_u32_e32 v137, vcc, 0, v159, vcc
	v_and_b32_e32 v141, 0xffff0000, v112
	v_cvt_pk_bf16_f32 v157, v142, v143
	global_store_dwordx4 v[136:137], v[154:157], off
	v_lshlrev_b32_e32 v112, 16, v113
	v_and_b32_e32 v113, 0xffff0000, v113
	v_pk_mul_f32 v[154:155], v[140:141], v[140:141]
	v_pk_mul_f32 v[156:157], v[112:113], v[112:113]
	v_add_f32_e32 v3, v154, v155
	v_lshlrev_b32_e32 v158, 16, v114
	v_and_b32_e32 v159, 0xffff0000, v114
	v_add_f32_e32 v3, v156, v3
	v_and_b32_e32 v142, 0xffff0000, v115
	v_lshlrev_b32_e32 v143, 16, v115
	v_pk_mul_f32 v[114:115], v[158:159], v[158:159]
	v_add_f32_e32 v3, v157, v3
	v_add_f32_e32 v3, v114, v3
	v_pk_mul_f32 v[138:139], v[142:143], v[142:143]
	v_add_f32_e32 v3, v115, v3
	v_add_f32_e32 v3, v139, v3
	v_add_f32_e32 v3, v138, v3
	ds_bpermute_b32 v5, v147, v3
	s_waitcnt lgkmcnt(0)
	v_add_f32_e32 v3, v3, v5
	ds_bpermute_b32 v5, v148, v3
	s_waitcnt lgkmcnt(0)
	v_add_f32_e32 v3, v3, v5
	ds_bpermute_b32 v5, v149, v3
	s_waitcnt lgkmcnt(0)
	v_add_f32_e32 v3, v3, v5
	ds_bpermute_b32 v5, v150, v3
	s_waitcnt lgkmcnt(0)
	v_add_f32_e32 v3, v3, v5
	v_fmamk_f32 v3, v3, 0x3c000000, v224
	v_cmp_gt_f32_e32 vcc, s33, v3
	v_mul_f32_e32 v5, 0x4f800000, v3
	s_nop 0
	v_cndmask_b32_e32 v3, v3, v5, vcc
	v_sqrt_f32_e32 v5, v3
	s_nop 0
	v_add_u32_e32 v7, -1, v5
	v_fma_f32 v9, -v7, v5, v3
	v_cmp_ge_f32_e64 s[48:49], 0, v9
	v_add_u32_e32 v9, 1, v5
	s_nop 0
	v_cndmask_b32_e64 v7, v5, v7, s[48:49]
	v_fma_f32 v5, -v9, v5, v3
	v_cmp_lt_f32_e64 s[48:49], 0, v5
	s_nop 1
	v_cndmask_b32_e64 v5, v7, v9, s[48:49]
	v_mul_f32_e32 v7, 0x37800000, v5
	v_cndmask_b32_e32 v5, v5, v7, vcc
	v_cmp_class_f32_e32 vcc, v3, v225
	s_nop 1
	v_cndmask_b32_e32 v3, v5, v3, vcc
	v_div_scale_f32 v5, s[6:7], v3, v3, 1.0
	v_rcp_f32_e32 v7, v5
	s_nop 0
	v_fma_f32 v9, -v5, v7, 1.0
	v_fmac_f32_e32 v7, v9, v7
	v_div_scale_f32 v9, vcc, 1.0, v3, 1.0
	v_mul_f32_e32 v11, v9, v7
	v_fma_f32 v13, -v5, v11, v9
	v_fmac_f32_e32 v11, v13, v7
	v_fma_f32 v5, -v5, v11, v9
	v_div_fmas_f32 v5, v5, v7, v11
	v_div_fixup_f32 v154, v5, v3, 1.0
	v_pk_mul_f32 v[112:113], v[154:155], v[112:113] op_sel_hi:[0,1]
	v_pk_mul_f32 v[114:115], v[154:155], v[140:141] op_sel_hi:[0,1]
	v_pk_mul_f32 v[138:139], v[48:49], v[112:113]
	v_pk_mul_f32 v[112:113], v[154:155], v[158:159] op_sel_hi:[0,1]
	v_pk_mul_f32 v[140:141], v[46:47], v[114:115]
	v_pk_mul_f32 v[114:115], v[42:43], v[112:113]
	v_pk_mul_f32 v[112:113], v[154:155], v[142:143] op_sel_hi:[0,1]
	v_pk_mul_f32 v[112:113], v[44:45], v[112:113] op_sel:[0,1] op_sel_hi:[1,0]
	s_and_b64 vcc, exec, s[46:47]
	s_cbranch_vccnz .LBB0_367
	ds_bpermute_b32 v142, v149, v140
	ds_bpermute_b32 v143, v149, v141
	v_mov_b32_e32 v156, v59
	v_mov_b32_e32 v157, v61
	v_mov_b32_e32 v154, v58
	v_mov_b32_e32 v155, v60
	s_waitcnt lgkmcnt(0)
	v_pk_mul_f32 v[142:143], v[156:157], v[142:143]
	v_mov_b32_e32 v156, v63
	v_cndmask_b32_e64 v143, v143, -v143, s[42:43]
	v_cndmask_b32_e64 v142, v142, -v142, s[42:43]
	v_pk_fma_f32 v[140:141], v[154:155], v[140:141], v[142:143]
	ds_bpermute_b32 v142, v149, v138
	ds_bpermute_b32 v143, v149, v139
	v_mov_b32_e32 v157, v65
	v_mov_b32_e32 v154, v62
	v_mov_b32_e32 v155, v64
	s_waitcnt lgkmcnt(0)
	v_pk_mul_f32 v[142:143], v[156:157], v[142:143]
	s_nop 0
	v_cndmask_b32_e64 v143, v143, -v143, s[42:43]
	v_cndmask_b32_e64 v142, v142, -v142, s[42:43]
	v_pk_fma_f32 v[138:139], v[154:155], v[138:139], v[142:143]
	ds_bpermute_b32 v142, v149, v114
	ds_bpermute_b32 v143, v149, v115
	v_mov_b32_e32 v156, v67
	v_mov_b32_e32 v157, v69
	v_mov_b32_e32 v154, v66
	v_mov_b32_e32 v155, v68
	s_waitcnt lgkmcnt(0)
	v_pk_mul_f32 v[142:143], v[156:157], v[142:143]
	v_mov_b32_e32 v156, v71
	v_cndmask_b32_e64 v143, v143, -v143, s[42:43]
	v_cndmask_b32_e64 v142, v142, -v142, s[42:43]
	v_pk_fma_f32 v[114:115], v[154:155], v[114:115], v[142:143]
	ds_bpermute_b32 v142, v149, v112
	ds_bpermute_b32 v143, v149, v113
	v_mov_b32_e32 v157, v73
	v_mov_b32_e32 v154, v70
	v_mov_b32_e32 v155, v72
	s_waitcnt lgkmcnt(0)
	v_pk_mul_f32 v[142:143], v[156:157], v[142:143]
	s_nop 0
	v_cndmask_b32_e64 v143, v143, -v143, s[42:43]
	v_cndmask_b32_e64 v142, v142, -v142, s[42:43]
	v_pk_fma_f32 v[112:113], v[154:155], v[112:113], v[142:143]
	s_branch .LBB0_367
